# E11: v50 + attention loop-edge bookkeeping moved ahead of the per-tile barriers
# baseline (speedup 1.0000x reference)
.LBB0_731:
	s_mov_b32 s44, s29
	s_mov_b32 s28, s25
	v_add_u32_e32 v195, s45, v190
	ds_read_b64_tr_b16 v[196:197], v195 offset:24576
	ds_read_b64_tr_b16 v[198:199], v195 offset:25088
	v_add_f32_e32 v88, v68, v69
	v_add_f32_e32 v88, v70, v88
	v_add_f32_e32 v88, v71, v88
	v_add_f32_e32 v88, v72, v88
	v_add_f32_e32 v88, v73, v88
	v_cvt_pk_bf16_f32 v152, v68, v69
	v_cvt_pk_bf16_f32 v153, v70, v71
	v_mfma_f32_32x32x16_bf16 v[100:115], v[84:87], v[160:163], v[36:51]
	ds_read_b64_tr_b16 v[68:69], v195 offset:28672
	ds_read_b64_tr_b16 v[70:71], v195 offset:29184
	v_add_f32_e32 v84, v74, v88
	v_add_f32_e32 v84, v75, v84
	v_add_f32_e32 v84, v76, v84
	v_add_f32_e32 v132, v77, v84
	v_mfma_f32_32x32x16_bf16 v[84:99], v[168:171], v[160:163], v[36:51]
	v_cvt_pk_bf16_f32 v154, v72, v73
	v_cvt_pk_bf16_f32 v155, v74, v75
	ds_read_b64_tr_b16 v[72:73], v195 offset:25600
	ds_read_b64_tr_b16 v[74:75], v195 offset:26112
	v_add_f32_e32 v132, v78, v132
	v_add_f32_e32 v132, v79, v132
	v_add_f32_e32 v132, v80, v132
	v_add_f32_e32 v132, v81, v132
	v_cvt_pk_bf16_f32 v148, v76, v77
	v_cvt_pk_bf16_f32 v149, v78, v79
	v_mfma_f32_32x32x16_bf16 v[100:115], v[172:175], v[156:159], v[100:115]
	ds_read_b64_tr_b16 v[76:77], v195 offset:29696
	ds_read_b64_tr_b16 v[78:79], v195 offset:30208
	v_mfma_f32_32x32x16_bf16 v[84:99], v[164:167], v[156:159], v[84:99]
	v_add_f32_e32 v132, v82, v132
	v_add_f32_e32 v132, v83, v132
	v_add_f32_e32 v132, v52, v132
	v_add_f32_e32 v132, v53, v132
	v_cvt_pk_bf16_f32 v150, v80, v81
	v_cvt_pk_bf16_f32 v151, v82, v83
	ds_read_b64_tr_b16 v[80:81], v195 offset:26624
	ds_read_b64_tr_b16 v[82:83], v195 offset:27136
	v_mfma_f32_32x32x16_bf16 v[100:115], v[128:131], v[144:147], v[100:115]
	v_add_f32_e32 v128, v54, v132
	v_add_f32_e32 v128, v55, v128
	v_add_f32_e32 v128, v56, v128
	v_add_f32_e32 v128, v57, v128
	v_cvt_pk_bf16_f32 v140, v52, v53
	v_cvt_pk_bf16_f32 v141, v54, v55
	ds_read_b64_tr_b16 v[52:53], v195 offset:30720
	ds_read_b64_tr_b16 v[54:55], v195 offset:31232
	v_mfma_f32_32x32x16_bf16 v[84:99], v[124:127], v[144:147], v[84:99]
	v_add_f32_e32 v124, v58, v128
	v_add_f32_e32 v124, v59, v124
	v_add_f32_e32 v124, v60, v124
	v_add_f32_e32 v124, v61, v124
	v_cvt_pk_bf16_f32 v142, v56, v57
	v_cvt_pk_bf16_f32 v143, v58, v59
	ds_read_b64_tr_b16 v[56:57], v195 offset:27648
	ds_read_b64_tr_b16 v[58:59], v195 offset:28160
	v_mfma_f32_32x32x16_bf16 v[100:115], v[120:123], v[136:139], v[100:115]
	v_add_f32_e32 v120, v62, v124
	v_add_f32_e32 v120, v63, v120
	v_add_f32_e32 v120, v64, v120
	v_add_f32_e32 v120, v65, v120
	v_cvt_pk_bf16_f32 v132, v60, v61
	v_cvt_pk_bf16_f32 v133, v62, v63
	ds_read_b64_tr_b16 v[60:61], v195 offset:31744
	ds_read_b64_tr_b16 v[62:63], v195 offset:32256
	v_mfma_f32_32x32x16_bf16 v[84:99], v[116:119], v[136:139], v[84:99]
	v_add_f32_e32 v116, v66, v120
	v_add_f32_e32 v195, v67, v116
	v_cvt_pk_bf16_f32 v134, v64, v65
	v_cvt_pk_bf16_f32 v135, v66, v67
	s_add_i32 m0, s25, s59
	v_lshl_add_u64 v[64:65], v[0:1], 0, s[76:77]
	global_load_lds_dwordx4 v[64:65], off
	s_add_i32 m0, s44, s58
	v_lshl_add_u64 v[64:65], v[184:185], 0, s[34:35]
	global_load_lds_dwordx4 v[64:65], off
	s_waitcnt lgkmcnt(14)
	v_mfma_f32_32x32x16_bf16 v[4:19], v[152:155], v[196:199], v[4:19]
	v_exp_f32_e32 v100, v100
	v_exp_f32_e32 v101, v101
	v_exp_f32_e32 v102, v102
	v_exp_f32_e32 v103, v103
	s_waitcnt lgkmcnt(12)
	v_mfma_f32_32x32x16_bf16 v[20:35], v[152:155], v[68:71], v[20:35]
	v_exp_f32_e32 v104, v104
	v_exp_f32_e32 v105, v105
	v_exp_f32_e32 v106, v106
	v_exp_f32_e32 v107, v107
	v_add_u32_e32 v68, s44, v191
	ds_read_b128 v[64:67], v68
	ds_read_b128 v[120:123], v68 offset:512
	s_waitcnt lgkmcnt(12)
	v_mfma_f32_32x32x16_bf16 v[4:19], v[148:151], v[72:75], v[4:19]
	v_exp_f32_e32 v108, v108
	v_exp_f32_e32 v109, v109
	v_exp_f32_e32 v110, v110
	v_exp_f32_e32 v111, v111
	ds_read_b128 v[124:127], v68 offset:2048
	ds_read_b128 v[128:131], v68 offset:2560
	s_waitcnt lgkmcnt(12)
	v_mfma_f32_32x32x16_bf16 v[20:35], v[148:151], v[76:79], v[20:35]
	v_exp_f32_e32 v112, v112
	v_exp_f32_e32 v113, v113
	v_exp_f32_e32 v114, v114
	v_exp_f32_e32 v115, v115
	ds_read_b128 v[164:167], v68 offset:4096
	ds_read_b128 v[168:171], v68 offset:4608
	s_waitcnt lgkmcnt(12)
	v_mfma_f32_32x32x16_bf16 v[4:19], v[140:143], v[80:83], v[4:19]
	v_exp_f32_e32 v84, v84
	v_exp_f32_e32 v85, v85
	v_exp_f32_e32 v86, v86
	v_exp_f32_e32 v87, v87
	ds_read_b128 v[172:175], v68 offset:6144
	ds_read_b128 v[116:119], v68 offset:6656
	s_waitcnt lgkmcnt(12)
	v_mfma_f32_32x32x16_bf16 v[20:35], v[140:143], v[52:55], v[20:35]
	v_exp_f32_e32 v88, v88
	v_exp_f32_e32 v89, v89
	v_exp_f32_e32 v90, v90
	v_exp_f32_e32 v91, v91
	s_waitcnt lgkmcnt(10)
	v_mfma_f32_32x32x16_bf16 v[4:19], v[132:135], v[56:59], v[4:19]
	v_exp_f32_e32 v92, v92
	v_exp_f32_e32 v93, v93
	v_exp_f32_e32 v94, v94
	v_exp_f32_e32 v95, v95
	s_waitcnt lgkmcnt(8)
	v_mfma_f32_32x32x16_bf16 v[20:35], v[132:135], v[60:63], v[20:35]
	v_exp_f32_e32 v96, v96
	v_exp_f32_e32 v97, v97
	v_exp_f32_e32 v98, v98
	v_exp_f32_e32 v99, v99
	s_add_i32 s25, s44, 0x2000
	s_cmpk_lg_i32 s44, 0x4000
	s_cselect_b32 s25, s25, 0
	s_waitcnt vmcnt(2) lgkmcnt(0)
	s_barrier
	v_add_u32_e32 v200, s28, v190
	ds_read_b64_tr_b16 v[196:197], v200 offset:24576
	ds_read_b64_tr_b16 v[198:199], v200 offset:25088
	v_mfma_f32_32x32x16_bf16 v[68:83], v[64:67], v[160:163], v[36:51]
	v_add_f32_e32 v52, v100, v101
	v_add_f32_e32 v52, v102, v52
	v_add_f32_e32 v52, v103, v52
	v_add_f32_e32 v52, v104, v52
	v_add_f32_e32 v52, v105, v52
	v_cvt_pk_bf16_f32 v152, v100, v101
	v_cvt_pk_bf16_f32 v153, v102, v103
	ds_read_b64_tr_b16 v[100:101], v200 offset:28672
	ds_read_b64_tr_b16 v[102:103], v200 offset:29184
	v_add_f32_e32 v52, v106, v52
	v_add_f32_e32 v52, v107, v52
	v_add_f32_e32 v52, v108, v52
	v_add_f32_e32 v132, v109, v52
	v_mfma_f32_32x32x16_bf16 v[52:67], v[120:123], v[160:163], v[36:51]
	v_cvt_pk_bf16_f32 v154, v104, v105
	v_cvt_pk_bf16_f32 v155, v106, v107
	ds_read_b64_tr_b16 v[104:105], v200 offset:25600
	ds_read_b64_tr_b16 v[106:107], v200 offset:26112
	v_mfma_f32_32x32x16_bf16 v[68:83], v[124:127], v[156:159], v[68:83]
	v_add_f32_e32 v120, v110, v132
	v_add_f32_e32 v120, v111, v120
	v_add_f32_e32 v120, v112, v120
	v_add_f32_e32 v120, v113, v120
	v_cvt_pk_bf16_f32 v148, v108, v109
	v_cvt_pk_bf16_f32 v149, v110, v111
	ds_read_b64_tr_b16 v[108:109], v200 offset:29696
	ds_read_b64_tr_b16 v[110:111], v200 offset:30208
	v_mfma_f32_32x32x16_bf16 v[52:67], v[128:131], v[156:159], v[52:67]
	v_add_f32_e32 v120, v114, v120
	v_add_f32_e32 v120, v115, v120
	v_add_f32_e32 v120, v84, v120
	v_add_f32_e32 v120, v85, v120
	v_cvt_pk_bf16_f32 v150, v112, v113
	v_cvt_pk_bf16_f32 v151, v114, v115
	ds_read_b64_tr_b16 v[112:113], v200 offset:26624
	ds_read_b64_tr_b16 v[114:115], v200 offset:27136
	v_mfma_f32_32x32x16_bf16 v[68:83], v[164:167], v[144:147], v[68:83]
	v_add_f32_e32 v120, v86, v120
	v_add_f32_e32 v120, v87, v120
	v_add_f32_e32 v120, v88, v120
	v_add_f32_e32 v120, v89, v120
	v_cvt_pk_bf16_f32 v140, v84, v85
	v_cvt_pk_bf16_f32 v141, v86, v87
	ds_read_b64_tr_b16 v[206:207], v200 offset:30720
	ds_read_b64_tr_b16 v[208:209], v200 offset:31232
	v_mfma_f32_32x32x16_bf16 v[52:67], v[168:171], v[144:147], v[52:67]
	v_add_f32_e32 v84, v90, v120
	v_add_f32_e32 v84, v91, v84
	v_add_f32_e32 v84, v92, v84
	v_add_f32_e32 v84, v93, v84
	v_cvt_pk_bf16_f32 v142, v88, v89
	v_cvt_pk_bf16_f32 v143, v90, v91
	ds_read_b64_tr_b16 v[88:89], v200 offset:27648
	ds_read_b64_tr_b16 v[90:91], v200 offset:28160
	v_mfma_f32_32x32x16_bf16 v[68:83], v[172:175], v[136:139], v[68:83]
	v_add_f32_e32 v84, v94, v84
	v_add_f32_e32 v84, v95, v84
	v_add_f32_e32 v84, v96, v84
	v_add_f32_e32 v84, v97, v84
	v_cvt_pk_bf16_f32 v132, v92, v93
	v_cvt_pk_bf16_f32 v133, v94, v95
	ds_read_b64_tr_b16 v[92:93], v200 offset:31744
	ds_read_b64_tr_b16 v[94:95], v200 offset:32256
	v_mfma_f32_32x32x16_bf16 v[52:67], v[116:119], v[136:139], v[52:67]
	v_add_f32_e32 v84, v98, v84
	v_add_f32_e32 v200, v99, v84
	v_cvt_pk_bf16_f32 v134, v96, v97
	v_cvt_pk_bf16_f32 v135, v98, v99
	s_mov_b64 s[28:29], 0x10000
	s_add_i32 m0, s44, s59
	v_lshl_add_u64 v[84:85], v[0:1], 0, s[28:29]
	global_load_lds_dwordx4 v[84:85], off
	s_add_i32 m0, s25, s58
	v_lshl_add_u64 v[184:185], v[184:185], 0, s[36:37]
	global_load_lds_dwordx4 v[184:185], off
	s_waitcnt lgkmcnt(14)
	v_mfma_f32_32x32x16_bf16 v[4:19], v[152:155], v[196:199], v[4:19]
	v_exp_f32_e32 v68, v68
	v_exp_f32_e32 v69, v69
	v_exp_f32_e32 v70, v70
	v_exp_f32_e32 v71, v71
	s_waitcnt lgkmcnt(12)
	v_mfma_f32_32x32x16_bf16 v[20:35], v[152:155], v[100:103], v[20:35]
	v_exp_f32_e32 v72, v72
	v_exp_f32_e32 v73, v73
	v_exp_f32_e32 v74, v74
	v_exp_f32_e32 v75, v75
	v_add_u32_e32 v96, s25, v191
	ds_read_b128 v[84:87], v96
	ds_read_b128 v[168:171], v96 offset:512
	s_waitcnt lgkmcnt(12)
	v_mfma_f32_32x32x16_bf16 v[4:19], v[148:151], v[104:107], v[4:19]
	v_exp_f32_e32 v76, v76
	v_exp_f32_e32 v77, v77
	v_exp_f32_e32 v78, v78
	v_exp_f32_e32 v79, v79
	ds_read_b128 v[172:175], v96 offset:2048
	ds_read_b128 v[164:167], v96 offset:2560
	s_waitcnt lgkmcnt(12)
	v_mfma_f32_32x32x16_bf16 v[20:35], v[148:151], v[108:111], v[20:35]
	v_exp_f32_e32 v80, v80
	v_exp_f32_e32 v81, v81
	v_exp_f32_e32 v82, v82
	v_exp_f32_e32 v83, v83
	ds_read_b128 v[128:131], v96 offset:4096
	ds_read_b128 v[124:127], v96 offset:4608
	s_waitcnt lgkmcnt(12)
	v_mfma_f32_32x32x16_bf16 v[4:19], v[140:143], v[112:115], v[4:19]
	v_exp_f32_e32 v52, v52
	v_exp_f32_e32 v53, v53
	v_exp_f32_e32 v54, v54
	v_exp_f32_e32 v55, v55
	ds_read_b128 v[120:123], v96 offset:6144
	ds_read_b128 v[116:119], v96 offset:6656
	s_waitcnt lgkmcnt(12)
	v_mfma_f32_32x32x16_bf16 v[20:35], v[140:143], v[206:209], v[20:35]
	v_exp_f32_e32 v56, v56
	v_exp_f32_e32 v57, v57
	v_exp_f32_e32 v58, v58
	v_exp_f32_e32 v59, v59
	s_waitcnt lgkmcnt(10)
	v_mfma_f32_32x32x16_bf16 v[4:19], v[132:135], v[88:91], v[4:19]
	v_exp_f32_e32 v60, v60
	v_exp_f32_e32 v61, v61
	v_exp_f32_e32 v62, v62
	v_exp_f32_e32 v63, v63
	s_waitcnt lgkmcnt(8)
	v_mfma_f32_32x32x16_bf16 v[20:35], v[132:135], v[92:95], v[20:35]
	v_exp_f32_e32 v64, v64
	v_exp_f32_e32 v65, v65
	v_exp_f32_e32 v66, v66
	v_exp_f32_e32 v67, v67
	s_add_i32 s28, s25, 0x2000
	s_cmpk_lg_i32 s25, 0x4000
	v_add_f32_e32 v88, v192, v195
	s_cselect_b32 s29, s28, 0
	s_add_i32 s24, s24, 2
	v_add_f32_e32 v192, v88, v200
	v_lshl_add_u64 v[0:1], v[0:1], 0, s[36:37]
	s_cmpk_gt_u32 s24, 0xf8
	s_mov_b32 s45, s44
	s_waitcnt vmcnt(2) lgkmcnt(0)
	s_barrier
	s_cbranch_scc0 .LBB0_731
	s_and_b32 s24, s60, 0x3fffffc0
	s_cmp_lg_u32 0, -1
	s_cselect_b32 s28, 0, 0
	s_addk_i32 s28, 0x6000
	s_lshl_b32 s24, s24, 2
	v_add3_u32 v0, v194, s28, v193
	s_add_i32 s28, s24, 0
	v_add_u32_e32 v1, s44, v190
	ds_read_b64_tr_b16 v[194:195], v1 offset:24576
	ds_read_b64_tr_b16 v[196:197], v1 offset:25088
	v_add_f32_e32 v88, v68, v69
	v_add_f32_e32 v88, v70, v88
	v_add_f32_e32 v88, v71, v88
	v_add_f32_e32 v88, v72, v88
	v_add_f32_e32 v88, v73, v88
	v_cvt_pk_bf16_f32 v152, v68, v69
	v_cvt_pk_bf16_f32 v153, v70, v71
	s_waitcnt lgkmcnt(9)
	v_mfma_f32_32x32x16_bf16 v[100:115], v[84:87], v[160:163], v[36:51]
	ds_read_b64_tr_b16 v[68:69], v1 offset:28672
	ds_read_b64_tr_b16 v[70:71], v1 offset:29184
	v_add_f32_e32 v84, v74, v88
	v_add_f32_e32 v84, v75, v84
	v_add_f32_e32 v84, v76, v84
	v_add_f32_e32 v132, v77, v84
	v_cvt_pk_bf16_f32 v154, v72, v73
	v_cvt_pk_bf16_f32 v155, v74, v75
	s_waitcnt lgkmcnt(10)
	v_mfma_f32_32x32x16_bf16 v[84:99], v[168:171], v[160:163], v[36:51]
	ds_read_b64_tr_b16 v[72:73], v1 offset:25600
	ds_read_b64_tr_b16 v[74:75], v1 offset:26112
	v_add_f32_e32 v132, v78, v132
	v_add_f32_e32 v132, v79, v132
	v_add_f32_e32 v132, v80, v132
	v_add_f32_e32 v132, v81, v132
	v_cvt_pk_bf16_f32 v148, v76, v77
	v_cvt_pk_bf16_f32 v149, v78, v79
	s_waitcnt lgkmcnt(11)
	v_mfma_f32_32x32x16_bf16 v[100:115], v[172:175], v[156:159], v[100:115]
	ds_read_b64_tr_b16 v[76:77], v1 offset:29696
	ds_read_b64_tr_b16 v[78:79], v1 offset:30208
	v_add_f32_e32 v132, v82, v132
	v_add_f32_e32 v132, v83, v132
	v_add_f32_e32 v132, v52, v132
	v_add_f32_e32 v132, v53, v132
	v_cvt_pk_bf16_f32 v150, v80, v81
	v_cvt_pk_bf16_f32 v151, v82, v83
	s_waitcnt lgkmcnt(12)
	v_mfma_f32_32x32x16_bf16 v[84:99], v[164:167], v[156:159], v[84:99]
	ds_read_b64_tr_b16 v[80:81], v1 offset:26624
	ds_read_b64_tr_b16 v[82:83], v1 offset:27136
	s_waitcnt lgkmcnt(13)
	v_mfma_f32_32x32x16_bf16 v[100:115], v[128:131], v[144:147], v[100:115]
	v_add_f32_e32 v128, v54, v132
	v_add_f32_e32 v128, v55, v128
	v_add_f32_e32 v128, v56, v128
	v_add_f32_e32 v128, v57, v128
	v_cvt_pk_bf16_f32 v140, v52, v53
	v_cvt_pk_bf16_f32 v141, v54, v55
	ds_read_b64_tr_b16 v[52:53], v1 offset:30720
	ds_read_b64_tr_b16 v[54:55], v1 offset:31232
	s_waitcnt lgkmcnt(14)
	v_mfma_f32_32x32x16_bf16 v[84:99], v[124:127], v[144:147], v[84:99]
	v_add_f32_e32 v124, v58, v128
	v_add_f32_e32 v124, v59, v124
	v_add_f32_e32 v124, v60, v124
	v_add_f32_e32 v124, v61, v124
	v_cvt_pk_bf16_f32 v142, v56, v57
	v_cvt_pk_bf16_f32 v143, v58, v59
	ds_read_b64_tr_b16 v[56:57], v1 offset:27648
	ds_read_b64_tr_b16 v[58:59], v1 offset:28160
	s_waitcnt lgkmcnt(14)
	v_mfma_f32_32x32x16_bf16 v[100:115], v[120:123], v[136:139], v[100:115]
	v_add_f32_e32 v120, v62, v124
	v_add_f32_e32 v120, v63, v120
	v_add_f32_e32 v120, v64, v120
	v_add_f32_e32 v120, v65, v120
	v_cvt_pk_bf16_f32 v132, v60, v61
	v_cvt_pk_bf16_f32 v133, v62, v63
	ds_read_b64_tr_b16 v[60:61], v1 offset:31744
	ds_read_b64_tr_b16 v[62:63], v1 offset:32256
	v_add_f32_e32 v1, v66, v120
	v_add_f32_e32 v1, v67, v1
	v_add_f32_e32 v1, 0, v1
	v_cvt_pk_bf16_f32 v134, v64, v65
	v_cvt_pk_bf16_f32 v135, v66, v67
	v_mfma_f32_32x32x16_bf16 v[84:99], v[116:119], v[136:139], v[84:99]
	s_mov_b64 s[46:47], 0x3f8000
	s_add_i32 s24, s25, s59
	v_lshl_add_u64 v[64:65], v[182:183], 0, s[46:47]
	s_mov_b32 s44, m0
	s_mov_b32 m0, s24
	s_nop 0
	global_load_lds_dwordx4 v[64:65], off
	s_mov_b32 m0, s44
	s_mov_b64 s[44:45], 0x3f0000
	v_lshl_add_u64 v[64:65], v[180:181], 0, s[44:45]
	s_add_i32 s24, s29, s58
	s_mov_b32 s44, m0
	s_mov_b32 m0, s24
	s_nop 0
	global_load_lds_dwordx4 v[64:65], off
	s_mov_b32 m0, s44
	v_add_f32_e32 v1, v192, v1
	s_waitcnt lgkmcnt(14)
	v_mfma_f32_32x32x16_bf16 v[4:19], v[152:155], v[194:197], v[4:19]
	v_exp_f32_e32 v100, v100
	v_exp_f32_e32 v101, v101
	v_exp_f32_e32 v102, v102
	v_exp_f32_e32 v103, v103
	s_waitcnt lgkmcnt(12)
	v_mfma_f32_32x32x16_bf16 v[20:35], v[152:155], v[68:71], v[20:35]
	v_exp_f32_e32 v104, v104
	v_exp_f32_e32 v105, v105
	v_exp_f32_e32 v106, v106
	v_exp_f32_e32 v107, v107
	v_add_u32_e32 v68, s29, v191
	ds_read_b128 v[64:67], v68
	ds_read_b128 v[164:167], v68 offset:512
	s_waitcnt lgkmcnt(12)
	v_mfma_f32_32x32x16_bf16 v[4:19], v[148:151], v[72:75], v[4:19]
	v_exp_f32_e32 v108, v108
	v_exp_f32_e32 v109, v109
	v_exp_f32_e32 v110, v110
	v_exp_f32_e32 v111, v111
	ds_read_b128 v[72:75], v68 offset:2048
	ds_read_b128 v[168:171], v68 offset:2560
	s_waitcnt lgkmcnt(12)
	v_mfma_f32_32x32x16_bf16 v[20:35], v[148:151], v[76:79], v[20:35]
	v_exp_f32_e32 v112, v112
	v_exp_f32_e32 v113, v113
	v_exp_f32_e32 v114, v114
	v_exp_f32_e32 v115, v115
	ds_read_b128 v[76:79], v68 offset:4096
	ds_read_b128 v[172:175], v68 offset:4608
	s_waitcnt lgkmcnt(12)
	v_mfma_f32_32x32x16_bf16 v[4:19], v[140:143], v[80:83], v[4:19]
	v_exp_f32_e32 v84, v84
	v_exp_f32_e32 v85, v85
	v_exp_f32_e32 v86, v86
	v_exp_f32_e32 v87, v87
	ds_read_b128 v[80:83], v68 offset:6144
	ds_read_b128 v[68:71], v68 offset:6656
	s_waitcnt lgkmcnt(12)
	v_mfma_f32_32x32x16_bf16 v[20:35], v[140:143], v[52:55], v[20:35]
	v_exp_f32_e32 v88, v88
	v_exp_f32_e32 v89, v89
	v_exp_f32_e32 v90, v90
	v_exp_f32_e32 v91, v91
	s_waitcnt lgkmcnt(10)
	v_mfma_f32_32x32x16_bf16 v[4:19], v[132:135], v[56:59], v[4:19]
	v_exp_f32_e32 v92, v92
	v_exp_f32_e32 v93, v93
	v_exp_f32_e32 v94, v94
	v_exp_f32_e32 v95, v95
	s_waitcnt lgkmcnt(8)
	v_mfma_f32_32x32x16_bf16 v[20:35], v[132:135], v[60:63], v[20:35]
	v_exp_f32_e32 v96, v96
	v_exp_f32_e32 v97, v97
	v_exp_f32_e32 v98, v98
	v_exp_f32_e32 v99, v99
	s_waitcnt vmcnt(2) lgkmcnt(0)
	s_barrier
	s_add_i32 s24, s29, 0x2000
	s_cmpk_lg_i32 s29, 0x4000
	s_cselect_b32 s44, s24, 0
	v_add_u32_e32 v184, s25, v190
	ds_read_b64_tr_b16 v[192:193], v184 offset:24576
	ds_read_b64_tr_b16 v[194:195], v184 offset:25088
	v_add_f32_e32 v52, v100, v101
	v_add_f32_e32 v52, v102, v52
	v_add_f32_e32 v52, v103, v52
	v_add_f32_e32 v52, v104, v52
	v_add_f32_e32 v52, v105, v52
	v_cvt_pk_bf16_f32 v152, v100, v101
	v_cvt_pk_bf16_f32 v153, v102, v103
	s_waitcnt lgkmcnt(9)
	v_mfma_f32_32x32x16_bf16 v[116:131], v[64:67], v[160:163], v[36:51]
	ds_read_b64_tr_b16 v[100:101], v184 offset:28672
	ds_read_b64_tr_b16 v[102:103], v184 offset:29184
	v_add_f32_e32 v52, v106, v52
	v_add_f32_e32 v52, v107, v52
	v_add_f32_e32 v52, v108, v52
	v_add_f32_e32 v132, v109, v52
	v_cvt_pk_bf16_f32 v154, v104, v105
	v_cvt_pk_bf16_f32 v155, v106, v107
	s_waitcnt lgkmcnt(10)
	v_mfma_f32_32x32x16_bf16 v[52:67], v[164:167], v[160:163], v[36:51]
	ds_read_b64_tr_b16 v[104:105], v184 offset:25600
	ds_read_b64_tr_b16 v[106:107], v184 offset:26112
	s_waitcnt lgkmcnt(11)
	v_mfma_f32_32x32x16_bf16 v[116:131], v[72:75], v[156:159], v[116:131]
	v_add_f32_e32 v72, v110, v132
	v_add_f32_e32 v72, v111, v72
	v_add_f32_e32 v72, v112, v72
	v_add_f32_e32 v132, v113, v72
	v_cvt_pk_bf16_f32 v148, v108, v109
	v_cvt_pk_bf16_f32 v149, v110, v111
	ds_read_b64_tr_b16 v[72:73], v184 offset:29696
	ds_read_b64_tr_b16 v[74:75], v184 offset:30208
	v_add_f32_e32 v108, v114, v132
	v_add_f32_e32 v108, v115, v108
	v_add_f32_e32 v108, v84, v108
	v_add_f32_e32 v132, v85, v108
	v_cvt_pk_bf16_f32 v150, v112, v113
	v_cvt_pk_bf16_f32 v151, v114, v115
	s_waitcnt lgkmcnt(12)
	v_mfma_f32_32x32x16_bf16 v[52:67], v[168:171], v[156:159], v[52:67]
	ds_read_b64_tr_b16 v[108:109], v184 offset:26624
	ds_read_b64_tr_b16 v[110:111], v184 offset:27136
	s_waitcnt lgkmcnt(13)
	v_mfma_f32_32x32x16_bf16 v[116:131], v[76:79], v[144:147], v[116:131]
	v_add_f32_e32 v76, v86, v132
	v_add_f32_e32 v76, v87, v76
	v_add_f32_e32 v76, v88, v76
	v_add_f32_e32 v112, v89, v76
	v_cvt_pk_bf16_f32 v140, v84, v85
	v_cvt_pk_bf16_f32 v141, v86, v87
	ds_read_b64_tr_b16 v[76:77], v184 offset:30720
	ds_read_b64_tr_b16 v[78:79], v184 offset:31232
	v_add_f32_e32 v84, v90, v112
	v_add_f32_e32 v84, v91, v84
	v_add_f32_e32 v84, v92, v84
	v_add_f32_e32 v84, v93, v84
	v_cvt_pk_bf16_f32 v142, v88, v89
	v_cvt_pk_bf16_f32 v143, v90, v91
	s_waitcnt lgkmcnt(14)
	v_mfma_f32_32x32x16_bf16 v[52:67], v[172:175], v[144:147], v[52:67]
	ds_read_b64_tr_b16 v[88:89], v184 offset:27648
	ds_read_b64_tr_b16 v[90:91], v184 offset:28160
	s_waitcnt lgkmcnt(14)
	v_mfma_f32_32x32x16_bf16 v[116:131], v[80:83], v[136:139], v[116:131]
	v_add_f32_e32 v80, v94, v84
	v_add_f32_e32 v80, v95, v80
	v_add_f32_e32 v80, v96, v80
	v_add_f32_e32 v84, v97, v80
	v_cvt_pk_bf16_f32 v132, v92, v93
	v_cvt_pk_bf16_f32 v133, v94, v95
	ds_read_b64_tr_b16 v[80:81], v184 offset:31744
	ds_read_b64_tr_b16 v[82:83], v184 offset:32256
	v_mfma_f32_32x32x16_bf16 v[52:67], v[68:71], v[136:139], v[52:67]
	v_add_f32_e32 v68, v98, v84
	v_add_f32_e32 v68, v99, v68
	v_add_f32_e32 v68, 0, v68
	v_cvt_pk_bf16_f32 v134, v96, v97
	v_cvt_pk_bf16_f32 v135, v98, v99
	s_mov_b64 s[60:61], 0x3fc000
	v_add_f32_e32 v1, v1, v68
	s_add_i32 s24, s29, s59
	v_lshl_add_u64 v[68:69], v[182:183], 0, s[60:61]
	s_mov_b32 s25, m0
	s_mov_b32 m0, s24
	s_nop 0
	global_load_lds_dwordx4 v[68:69], off
	s_mov_b32 m0, s25
	s_mov_b64 s[24:25], 0x3f4000
	s_add_i32 s45, s44, s58
	v_lshl_add_u64 v[68:69], v[180:181], 0, s[24:25]
	s_mov_b32 s24, m0
	s_mov_b32 m0, s45
	s_nop 0
	global_load_lds_dwordx4 v[68:69], off
	s_mov_b32 m0, s24
	s_waitcnt lgkmcnt(14)
	v_mfma_f32_32x32x16_bf16 v[4:19], v[152:155], v[192:195], v[4:19]
	v_exp_f32_e32 v116, v116
	v_exp_f32_e32 v117, v117
	v_exp_f32_e32 v118, v118
	v_exp_f32_e32 v119, v119
	s_waitcnt lgkmcnt(12)
	v_mfma_f32_32x32x16_bf16 v[20:35], v[152:155], v[100:103], v[20:35]
	v_exp_f32_e32 v120, v120
	v_exp_f32_e32 v121, v121
	v_exp_f32_e32 v122, v122
	v_exp_f32_e32 v123, v123
	v_add_u32_e32 v84, s44, v191
	ds_read_b128 v[68:71], v84
	ds_read_b128 v[92:95], v84 offset:512
	s_waitcnt lgkmcnt(12)
	v_mfma_f32_32x32x16_bf16 v[4:19], v[148:151], v[104:107], v[4:19]
	v_exp_f32_e32 v124, v124
	v_exp_f32_e32 v125, v125
	v_exp_f32_e32 v126, v126
	v_exp_f32_e32 v127, v127
	ds_read_b128 v[96:99], v84 offset:2048
	ds_read_b128 v[164:167], v84 offset:2560
	s_waitcnt lgkmcnt(12)
	v_mfma_f32_32x32x16_bf16 v[20:35], v[148:151], v[72:75], v[20:35]
	v_exp_f32_e32 v128, v128
	v_exp_f32_e32 v129, v129
	v_exp_f32_e32 v130, v130
	v_exp_f32_e32 v131, v131
	ds_read_b128 v[168:171], v84 offset:4096
	ds_read_b128 v[172:175], v84 offset:4608
	s_waitcnt lgkmcnt(12)
	v_mfma_f32_32x32x16_bf16 v[4:19], v[140:143], v[108:111], v[4:19]
	v_exp_f32_e32 v52, v52
	v_exp_f32_e32 v53, v53
	v_exp_f32_e32 v54, v54
	v_exp_f32_e32 v55, v55
	ds_read_b128 v[182:185], v84 offset:6144
	ds_read_b128 v[84:87], v84 offset:6656
	s_waitcnt lgkmcnt(12)
	v_mfma_f32_32x32x16_bf16 v[20:35], v[140:143], v[76:79], v[20:35]
	v_exp_f32_e32 v56, v56
	v_exp_f32_e32 v57, v57
	v_exp_f32_e32 v58, v58
	v_exp_f32_e32 v59, v59
	s_waitcnt lgkmcnt(10)
	v_mfma_f32_32x32x16_bf16 v[4:19], v[132:135], v[88:91], v[4:19]
	v_exp_f32_e32 v60, v60
	v_exp_f32_e32 v61, v61
	v_exp_f32_e32 v62, v62
	v_exp_f32_e32 v63, v63
	s_waitcnt lgkmcnt(8)
	v_mfma_f32_32x32x16_bf16 v[20:35], v[132:135], v[80:83], v[20:35]
	v_exp_f32_e32 v64, v64
	v_exp_f32_e32 v65, v65
	v_exp_f32_e32 v66, v66
	v_exp_f32_e32 v67, v67
	s_waitcnt vmcnt(2) lgkmcnt(0)
	s_barrier
	s_add_i32 s24, s44, 0x2000
	s_cmpk_lg_i32 s44, 0x4000
	s_cselect_b32 s25, s24, 0
	v_add_u32_e32 v192, s29, v190
	ds_read_b64_tr_b16 v[88:89], v192 offset:24576
	ds_read_b64_tr_b16 v[90:91], v192 offset:25088
	v_add_f32_e32 v72, v116, v117
	v_add_f32_e32 v72, v118, v72
	v_add_f32_e32 v72, v119, v72
	v_add_f32_e32 v72, v120, v72
	v_add_f32_e32 v72, v121, v72
	v_cvt_pk_bf16_f32 v152, v116, v117
	v_cvt_pk_bf16_f32 v153, v118, v119
	s_waitcnt lgkmcnt(9)
	v_mfma_f32_32x32x16_bf16 v[100:115], v[68:71], v[160:163], v[36:51]
	ds_read_b64_tr_b16 v[116:117], v192 offset:28672
	ds_read_b64_tr_b16 v[118:119], v192 offset:29184
	v_add_f32_e32 v68, v122, v72
	v_add_f32_e32 v68, v123, v68
	v_add_f32_e32 v68, v124, v68
	v_add_f32_e32 v132, v125, v68
	v_cvt_pk_bf16_f32 v154, v120, v121
	v_cvt_pk_bf16_f32 v155, v122, v123
	s_waitcnt lgkmcnt(10)
	v_mfma_f32_32x32x16_bf16 v[68:83], v[92:95], v[160:163], v[36:51]
	ds_read_b64_tr_b16 v[92:93], v192 offset:25600
	ds_read_b64_tr_b16 v[94:95], v192 offset:26112
	s_waitcnt lgkmcnt(11)
	v_mfma_f32_32x32x16_bf16 v[100:115], v[96:99], v[156:159], v[100:115]
	v_add_f32_e32 v96, v126, v132
	v_add_f32_e32 v96, v127, v96
	v_add_f32_e32 v96, v128, v96
	v_add_f32_e32 v120, v129, v96
	v_cvt_pk_bf16_f32 v148, v124, v125
	v_cvt_pk_bf16_f32 v149, v126, v127
	ds_read_b64_tr_b16 v[96:97], v192 offset:29696
	ds_read_b64_tr_b16 v[98:99], v192 offset:30208
	v_add_f32_e32 v120, v130, v120
	v_add_f32_e32 v120, v131, v120
	v_add_f32_e32 v120, v52, v120
	v_add_f32_e32 v124, v53, v120
	v_cvt_pk_bf16_f32 v150, v128, v129
	v_cvt_pk_bf16_f32 v151, v130, v131
	s_waitcnt lgkmcnt(12)
	v_mfma_f32_32x32x16_bf16 v[68:83], v[164:167], v[156:159], v[68:83]
	ds_read_b64_tr_b16 v[120:121], v192 offset:26624
	ds_read_b64_tr_b16 v[122:123], v192 offset:27136
	v_add_f32_e32 v124, v54, v124
	v_add_f32_e32 v124, v55, v124
	v_add_f32_e32 v124, v56, v124
	v_add_f32_e32 v124, v57, v124
	v_cvt_pk_bf16_f32 v140, v52, v53
	v_cvt_pk_bf16_f32 v141, v54, v55
	s_waitcnt lgkmcnt(13)
	v_mfma_f32_32x32x16_bf16 v[100:115], v[168:171], v[144:147], v[100:115]
	ds_read_b64_tr_b16 v[52:53], v192 offset:30720
	ds_read_b64_tr_b16 v[54:55], v192 offset:31232
	v_add_f32_e32 v124, v58, v124
	v_add_f32_e32 v124, v59, v124
	v_add_f32_e32 v124, v60, v124
	v_add_f32_e32 v124, v61, v124
	v_cvt_pk_bf16_f32 v142, v56, v57
	v_cvt_pk_bf16_f32 v143, v58, v59
	s_waitcnt lgkmcnt(14)
	v_mfma_f32_32x32x16_bf16 v[68:83], v[172:175], v[144:147], v[68:83]
	ds_read_b64_tr_b16 v[56:57], v192 offset:27648
	ds_read_b64_tr_b16 v[58:59], v192 offset:28160
	v_add_f32_e32 v124, v62, v124
	v_add_f32_e32 v124, v63, v124
	v_add_f32_e32 v124, v64, v124
	v_add_f32_e32 v124, v65, v124
	v_cvt_pk_bf16_f32 v132, v60, v61
	v_cvt_pk_bf16_f32 v133, v62, v63
	s_waitcnt lgkmcnt(14)
	v_mfma_f32_32x32x16_bf16 v[100:115], v[182:185], v[136:139], v[100:115]
	ds_read_b64_tr_b16 v[60:61], v192 offset:31744
	ds_read_b64_tr_b16 v[62:63], v192 offset:32256
	v_mfma_f32_32x32x16_bf16 v[68:83], v[84:87], v[136:139], v[68:83]
	v_add_f32_e32 v84, v66, v124
	v_add_f32_e32 v84, v67, v84
	v_add_f32_e32 v84, 0, v84
	v_cvt_pk_bf16_f32 v134, v64, v65
	v_cvt_pk_bf16_f32 v135, v66, v67
	v_lshl_add_u64 v[64:65], v[180:181], 0, s[46:47]
	s_add_i32 s24, s25, s58
	s_mov_b32 s29, m0
	s_mov_b32 m0, s24
	s_nop 0
	global_load_lds_dwordx4 v[64:65], off
	s_mov_b32 m0, s29
	v_add_f32_e32 v1, v1, v84
	s_waitcnt lgkmcnt(14)
	v_mfma_f32_32x32x16_bf16 v[4:19], v[152:155], v[88:91], v[4:19]
	v_exp_f32_e32 v100, v100
	v_exp_f32_e32 v101, v101
	v_exp_f32_e32 v102, v102
	v_exp_f32_e32 v103, v103
	s_waitcnt lgkmcnt(12)
	v_mfma_f32_32x32x16_bf16 v[20:35], v[152:155], v[116:119], v[20:35]
	v_exp_f32_e32 v104, v104
	v_exp_f32_e32 v105, v105
	v_exp_f32_e32 v106, v106
	v_exp_f32_e32 v107, v107
	v_add_u32_e32 v84, s25, v191
	ds_read_b128 v[64:67], v84
	ds_read_b128 v[124:127], v84 offset:512
	s_waitcnt lgkmcnt(12)
	v_mfma_f32_32x32x16_bf16 v[4:19], v[148:151], v[92:95], v[4:19]
	v_exp_f32_e32 v108, v108
	v_exp_f32_e32 v109, v109
	v_exp_f32_e32 v110, v110
	v_exp_f32_e32 v111, v111
	ds_read_b128 v[128:131], v84 offset:2048
	ds_read_b128 v[164:167], v84 offset:2560
	s_waitcnt lgkmcnt(12)
	v_mfma_f32_32x32x16_bf16 v[20:35], v[148:151], v[96:99], v[20:35]
	v_exp_f32_e32 v112, v112
	v_exp_f32_e32 v113, v113
	v_exp_f32_e32 v114, v114
	v_exp_f32_e32 v115, v115
	ds_read_b128 v[168:171], v84 offset:4096
	ds_read_b128 v[172:175], v84 offset:4608
	s_waitcnt lgkmcnt(12)
	v_mfma_f32_32x32x16_bf16 v[4:19], v[140:143], v[120:123], v[4:19]
	v_exp_f32_e32 v68, v68
	v_exp_f32_e32 v69, v69
	v_exp_f32_e32 v70, v70
	v_exp_f32_e32 v71, v71
	ds_read_b128 v[120:123], v84 offset:6144
	ds_read_b128 v[116:119], v84 offset:6656
	s_waitcnt lgkmcnt(12)
	v_mfma_f32_32x32x16_bf16 v[20:35], v[140:143], v[52:55], v[20:35]
	v_exp_f32_e32 v72, v72
	v_exp_f32_e32 v73, v73
	v_exp_f32_e32 v74, v74
	v_exp_f32_e32 v75, v75
	s_waitcnt lgkmcnt(10)
	v_mfma_f32_32x32x16_bf16 v[4:19], v[132:135], v[56:59], v[4:19]
	v_exp_f32_e32 v76, v76
	v_exp_f32_e32 v77, v77
	v_exp_f32_e32 v78, v78
	v_exp_f32_e32 v79, v79
	s_waitcnt lgkmcnt(8)
	v_mfma_f32_32x32x16_bf16 v[20:35], v[132:135], v[60:63], v[20:35]
	v_exp_f32_e32 v80, v80
	v_exp_f32_e32 v81, v81
	v_exp_f32_e32 v82, v82
	v_exp_f32_e32 v83, v83
	s_waitcnt vmcnt(1) lgkmcnt(0)
	s_barrier
	s_add_i32 s24, s25, 0x2000
	s_cmpk_lg_i32 s25, 0x4000
	s_cselect_b32 s24, s24, 0
	v_add_u32_e32 v192, s44, v190
	ds_read_b64_tr_b16 v[182:183], v192 offset:24576
	ds_read_b64_tr_b16 v[184:185], v192 offset:25088
	v_add_f32_e32 v52, v100, v101
	v_add_f32_e32 v52, v102, v52
	v_add_f32_e32 v52, v103, v52
	v_add_f32_e32 v52, v104, v52
	v_add_f32_e32 v52, v105, v52
	v_cvt_pk_bf16_f32 v152, v100, v101
	v_cvt_pk_bf16_f32 v153, v102, v103
	s_waitcnt lgkmcnt(9)
	v_mfma_f32_32x32x16_bf16 v[84:99], v[64:67], v[160:163], v[36:51]
	ds_read_b64_tr_b16 v[100:101], v192 offset:28672
	ds_read_b64_tr_b16 v[102:103], v192 offset:29184
	v_add_f32_e32 v52, v106, v52
	v_add_f32_e32 v52, v107, v52
	v_add_f32_e32 v52, v108, v52
	v_add_f32_e32 v132, v109, v52
	v_cvt_pk_bf16_f32 v154, v104, v105
	v_cvt_pk_bf16_f32 v155, v106, v107
	s_waitcnt lgkmcnt(10)
	v_mfma_f32_32x32x16_bf16 v[52:67], v[124:127], v[160:163], v[36:51]
	ds_read_b64_tr_b16 v[104:105], v192 offset:25600
	ds_read_b64_tr_b16 v[106:107], v192 offset:26112
	v_add_f32_e32 v124, v110, v132
	v_add_f32_e32 v124, v111, v124
	v_add_f32_e32 v124, v112, v124
	v_add_f32_e32 v124, v113, v124
	v_cvt_pk_bf16_f32 v148, v108, v109
	v_cvt_pk_bf16_f32 v149, v110, v111
	s_waitcnt lgkmcnt(11)
	v_mfma_f32_32x32x16_bf16 v[84:99], v[128:131], v[156:159], v[84:99]
	ds_read_b64_tr_b16 v[108:109], v192 offset:29696
	ds_read_b64_tr_b16 v[110:111], v192 offset:30208
	v_add_f32_e32 v124, v114, v124
	v_add_f32_e32 v124, v115, v124
	v_add_f32_e32 v124, v68, v124
	v_add_f32_e32 v124, v69, v124
	v_cvt_pk_bf16_f32 v150, v112, v113
	v_cvt_pk_bf16_f32 v151, v114, v115
	s_waitcnt lgkmcnt(12)
	v_mfma_f32_32x32x16_bf16 v[52:67], v[164:167], v[156:159], v[52:67]
	ds_read_b64_tr_b16 v[112:113], v192 offset:26624
	ds_read_b64_tr_b16 v[114:115], v192 offset:27136
	v_add_f32_e32 v124, v70, v124
	v_add_f32_e32 v124, v71, v124
	v_add_f32_e32 v124, v72, v124
	v_add_f32_e32 v124, v73, v124
	v_cvt_pk_bf16_f32 v140, v68, v69
	v_cvt_pk_bf16_f32 v141, v70, v71
	s_waitcnt lgkmcnt(13)
	v_mfma_f32_32x32x16_bf16 v[84:99], v[168:171], v[144:147], v[84:99]
	ds_read_b64_tr_b16 v[68:69], v192 offset:30720
	ds_read_b64_tr_b16 v[70:71], v192 offset:31232
	v_add_f32_e32 v124, v74, v124
	v_add_f32_e32 v124, v75, v124
	v_add_f32_e32 v124, v76, v124
	v_add_f32_e32 v124, v77, v124
	v_cvt_pk_bf16_f32 v142, v72, v73
	v_cvt_pk_bf16_f32 v143, v74, v75
	s_waitcnt lgkmcnt(14)
	v_mfma_f32_32x32x16_bf16 v[52:67], v[172:175], v[144:147], v[52:67]
	ds_read_b64_tr_b16 v[72:73], v192 offset:27648
	ds_read_b64_tr_b16 v[74:75], v192 offset:28160
	s_waitcnt lgkmcnt(14)
	v_mfma_f32_32x32x16_bf16 v[84:99], v[120:123], v[136:139], v[84:99]
	v_add_f32_e32 v120, v78, v124
	v_add_f32_e32 v120, v79, v120
	v_add_f32_e32 v120, v80, v120
	v_add_f32_e32 v120, v81, v120
	v_cvt_pk_bf16_f32 v132, v76, v77
	v_cvt_pk_bf16_f32 v133, v78, v79
	ds_read_b64_tr_b16 v[76:77], v192 offset:31744
	ds_read_b64_tr_b16 v[78:79], v192 offset:32256
	v_mfma_f32_32x32x16_bf16 v[52:67], v[116:119], v[136:139], v[52:67]
	v_add_f32_e32 v116, v82, v120
	v_add_f32_e32 v116, v83, v116
	v_add_f32_e32 v116, 0, v116
	v_cvt_pk_bf16_f32 v134, v80, v81
	v_cvt_pk_bf16_f32 v135, v82, v83
	s_add_i32 s29, s24, s58
	v_lshl_add_u64 v[80:81], v[180:181], 0, s[60:61]
	s_mov_b32 s44, m0
	s_mov_b32 m0, s29
	s_nop 0
	global_load_lds_dwordx4 v[80:81], off
	s_mov_b32 m0, s44
	v_add_f32_e32 v1, v1, v116
	s_waitcnt lgkmcnt(14)
	v_mfma_f32_32x32x16_bf16 v[4:19], v[152:155], v[182:185], v[4:19]
	v_exp_f32_e32 v84, v84
	v_exp_f32_e32 v85, v85
	v_exp_f32_e32 v86, v86
	v_exp_f32_e32 v87, v87
	s_waitcnt lgkmcnt(12)
	v_mfma_f32_32x32x16_bf16 v[20:35], v[152:155], v[100:103], v[20:35]
	v_exp_f32_e32 v88, v88
	v_exp_f32_e32 v89, v89
	v_exp_f32_e32 v90, v90
	v_exp_f32_e32 v91, v91
	v_add_u32_e32 v80, s24, v191
	ds_read_b128 v[116:119], v80
	ds_read_b128 v[120:123], v80 offset:512
	s_waitcnt lgkmcnt(12)
	v_mfma_f32_32x32x16_bf16 v[4:19], v[148:151], v[104:107], v[4:19]
	v_exp_f32_e32 v92, v92
	v_exp_f32_e32 v93, v93
	v_exp_f32_e32 v94, v94
	v_exp_f32_e32 v95, v95
	ds_read_b128 v[104:107], v80 offset:2048
	ds_read_b128 v[124:127], v80 offset:2560
	s_waitcnt lgkmcnt(12)
	v_mfma_f32_32x32x16_bf16 v[20:35], v[148:151], v[108:111], v[20:35]
	v_exp_f32_e32 v96, v96
	v_exp_f32_e32 v97, v97
	v_exp_f32_e32 v98, v98
	v_exp_f32_e32 v99, v99
	ds_read_b128 v[108:111], v80 offset:4096
	ds_read_b128 v[128:131], v80 offset:4608
	s_waitcnt lgkmcnt(12)
	v_mfma_f32_32x32x16_bf16 v[4:19], v[140:143], v[112:115], v[4:19]
	v_exp_f32_e32 v52, v52
	v_exp_f32_e32 v53, v53
	v_exp_f32_e32 v54, v54
	v_exp_f32_e32 v55, v55
	ds_read_b128 v[112:115], v80 offset:6144
	ds_read_b128 v[100:103], v80 offset:6656
	s_waitcnt lgkmcnt(12)
	v_mfma_f32_32x32x16_bf16 v[20:35], v[140:143], v[68:71], v[20:35]
	v_exp_f32_e32 v56, v56
	v_exp_f32_e32 v57, v57
	v_exp_f32_e32 v58, v58
	v_exp_f32_e32 v59, v59
	s_waitcnt lgkmcnt(10)
	v_mfma_f32_32x32x16_bf16 v[4:19], v[132:135], v[72:75], v[4:19]
	v_exp_f32_e32 v60, v60
	v_exp_f32_e32 v61, v61
	v_exp_f32_e32 v62, v62
	v_exp_f32_e32 v63, v63
	s_waitcnt lgkmcnt(8)
	v_mfma_f32_32x32x16_bf16 v[20:35], v[132:135], v[76:79], v[20:35]
	v_exp_f32_e32 v64, v64
	v_exp_f32_e32 v65, v65
	v_exp_f32_e32 v66, v66
	v_exp_f32_e32 v67, v67
	s_waitcnt vmcnt(0) lgkmcnt(0)
	s_barrier
	v_add_u32_e32 v168, s25, v190
	ds_read_b64_tr_b16 v[164:165], v168 offset:24576
	ds_read_b64_tr_b16 v[166:167], v168 offset:25088
	v_add_f32_e32 v68, v84, v85
	v_add_f32_e32 v68, v86, v68
	v_add_f32_e32 v68, v87, v68
	v_add_f32_e32 v68, v88, v68
	v_add_f32_e32 v132, v89, v68
	v_cvt_pk_bf16_f32 v152, v84, v85
	v_cvt_pk_bf16_f32 v153, v86, v87
	s_waitcnt lgkmcnt(9)
	v_mfma_f32_32x32x16_bf16 v[68:83], v[116:119], v[160:163], v[36:51]
	ds_read_b64_tr_b16 v[84:85], v168 offset:28672
	ds_read_b64_tr_b16 v[86:87], v168 offset:29184
	v_add_f32_e32 v116, v90, v132
	v_add_f32_e32 v116, v91, v116
	v_add_f32_e32 v116, v92, v116
	v_add_f32_e32 v116, v93, v116
	v_cvt_pk_bf16_f32 v154, v88, v89
	v_cvt_pk_bf16_f32 v155, v90, v91
	s_waitcnt lgkmcnt(10)
	v_mfma_f32_32x32x16_bf16 v[36:51], v[120:123], v[160:163], v[36:51]
	ds_read_b64_tr_b16 v[88:89], v168 offset:25600
	ds_read_b64_tr_b16 v[90:91], v168 offset:26112
	s_waitcnt lgkmcnt(11)
	v_mfma_f32_32x32x16_bf16 v[68:83], v[104:107], v[156:159], v[68:83]
	v_add_f32_e32 v104, v94, v116
	v_add_f32_e32 v104, v95, v104
	v_add_f32_e32 v104, v96, v104
	v_add_f32_e32 v104, v97, v104
	v_cvt_pk_bf16_f32 v148, v92, v93
	v_cvt_pk_bf16_f32 v149, v94, v95
	ds_read_b64_tr_b16 v[92:93], v168 offset:29696
	ds_read_b64_tr_b16 v[94:95], v168 offset:30208
	v_add_f32_e32 v104, v98, v104
	v_add_f32_e32 v104, v99, v104
	v_add_f32_e32 v104, v52, v104
	v_add_f32_e32 v104, v53, v104
	v_cvt_pk_bf16_f32 v150, v96, v97
	v_cvt_pk_bf16_f32 v151, v98, v99
	s_waitcnt lgkmcnt(12)
	v_mfma_f32_32x32x16_bf16 v[36:51], v[124:127], v[156:159], v[36:51]
	ds_read_b64_tr_b16 v[96:97], v168 offset:26624
	ds_read_b64_tr_b16 v[98:99], v168 offset:27136
	v_add_f32_e32 v104, v54, v104
	v_add_f32_e32 v104, v55, v104
	v_add_f32_e32 v104, v56, v104
	v_add_f32_e32 v104, v57, v104
	v_cvt_pk_bf16_f32 v140, v52, v53
	v_cvt_pk_bf16_f32 v141, v54, v55
	s_waitcnt lgkmcnt(13)
	v_mfma_f32_32x32x16_bf16 v[68:83], v[108:111], v[144:147], v[68:83]
	ds_read_b64_tr_b16 v[52:53], v168 offset:30720
	ds_read_b64_tr_b16 v[54:55], v168 offset:31232
	v_add_f32_e32 v104, v58, v104
	v_add_f32_e32 v104, v59, v104
	v_add_f32_e32 v104, v60, v104
	v_add_f32_e32 v104, v61, v104
	v_cvt_pk_bf16_f32 v142, v56, v57
	v_cvt_pk_bf16_f32 v143, v58, v59
	s_waitcnt lgkmcnt(14)
	v_mfma_f32_32x32x16_bf16 v[36:51], v[128:131], v[144:147], v[36:51]
	ds_read_b64_tr_b16 v[56:57], v168 offset:27648
	ds_read_b64_tr_b16 v[58:59], v168 offset:28160
	v_add_f32_e32 v104, v62, v104
	v_add_f32_e32 v104, v63, v104
	v_add_f32_e32 v104, v64, v104
	v_add_f32_e32 v104, v65, v104
	v_cvt_pk_bf16_f32 v132, v60, v61
	v_cvt_pk_bf16_f32 v133, v62, v63
	s_waitcnt lgkmcnt(14)
	v_mfma_f32_32x32x16_bf16 v[68:83], v[112:115], v[136:139], v[68:83]
	ds_read_b64_tr_b16 v[60:61], v168 offset:31744
	ds_read_b64_tr_b16 v[62:63], v168 offset:32256
	v_mfma_f32_32x32x16_bf16 v[36:51], v[100:103], v[136:139], v[36:51]
	v_add_f32_e32 v100, v66, v104
	v_add_f32_e32 v100, v67, v100
	v_add_f32_e32 v100, 0, v100
	v_cvt_pk_bf16_f32 v134, v64, v65
	v_cvt_pk_bf16_f32 v135, v66, v67
	s_waitcnt lgkmcnt(14)
	v_mfma_f32_32x32x16_bf16 v[4:19], v[152:155], v[164:167], v[4:19]
	s_nop 1
	v_exp_f32_e32 v68, v68
	v_exp_f32_e32 v69, v69
	v_exp_f32_e32 v70, v70
	v_exp_f32_e32 v71, v71
	s_waitcnt lgkmcnt(12)
	v_mfma_f32_32x32x16_bf16 v[20:35], v[152:155], v[84:87], v[20:35]
	v_exp_f32_e32 v72, v72
	v_exp_f32_e32 v73, v73
	v_exp_f32_e32 v74, v74
	v_exp_f32_e32 v75, v75
	s_waitcnt lgkmcnt(10)
	v_mfma_f32_32x32x16_bf16 v[4:19], v[148:151], v[88:91], v[4:19]
	v_exp_f32_e32 v76, v76
	v_exp_f32_e32 v77, v77
	v_exp_f32_e32 v78, v78
	v_exp_f32_e32 v79, v79
	s_waitcnt lgkmcnt(8)
	v_mfma_f32_32x32x16_bf16 v[20:35], v[148:151], v[92:95], v[20:35]
	v_exp_f32_e32 v80, v80
	v_exp_f32_e32 v81, v81
	v_exp_f32_e32 v82, v82
	v_exp_f32_e32 v83, v83
	s_waitcnt lgkmcnt(6)
	v_mfma_f32_32x32x16_bf16 v[4:19], v[140:143], v[96:99], v[4:19]
	v_exp_f32_e32 v36, v36
	v_exp_f32_e32 v37, v37
	v_exp_f32_e32 v38, v38
	v_exp_f32_e32 v39, v39
	s_waitcnt lgkmcnt(4)
	v_mfma_f32_32x32x16_bf16 v[20:35], v[140:143], v[52:55], v[20:35]
	v_exp_f32_e32 v40, v40
	v_exp_f32_e32 v41, v41
	v_exp_f32_e32 v42, v42
	v_exp_f32_e32 v43, v43
	s_waitcnt lgkmcnt(2)
	v_mfma_f32_32x32x16_bf16 v[4:19], v[132:135], v[56:59], v[4:19]
	v_exp_f32_e32 v44, v44
	v_exp_f32_e32 v45, v45
	v_exp_f32_e32 v46, v46
	v_exp_f32_e32 v47, v47
	s_waitcnt lgkmcnt(0)
	v_mfma_f32_32x32x16_bf16 v[20:35], v[132:135], v[60:63], v[20:35]
	v_exp_f32_e32 v48, v48
	v_exp_f32_e32 v49, v49
	v_exp_f32_e32 v50, v50
	v_exp_f32_e32 v51, v51
	v_add_f32_e32 v52, v68, v69
	v_add_f32_e32 v52, v70, v52
	v_add_f32_e32 v52, v71, v52
	v_add_f32_e32 v52, v72, v52
	v_add_f32_e32 v52, v73, v52
	v_add_f32_e32 v52, v74, v52
	v_add_f32_e32 v52, v75, v52
	v_add_f32_e32 v52, v76, v52
	v_add_f32_e32 v52, v77, v52
	v_add_f32_e32 v52, v78, v52
	v_add_f32_e32 v52, v79, v52
	v_add_f32_e32 v52, v80, v52
	v_add_f32_e32 v52, v81, v52
	v_add_f32_e32 v52, v82, v52
	v_add_f32_e32 v52, v83, v52
	v_add_f32_e32 v52, v36, v52
	v_add_f32_e32 v52, v37, v52
	v_add_f32_e32 v52, v38, v52
	v_add_f32_e32 v52, v39, v52
	v_add_f32_e32 v52, v40, v52
	v_add_f32_e32 v52, v41, v52
	v_add_f32_e32 v52, v42, v52
	v_add_f32_e32 v52, v43, v52
	v_add_f32_e32 v52, v44, v52
	v_add_f32_e32 v52, v45, v52
	v_add_f32_e32 v52, v46, v52
	v_add_f32_e32 v52, v47, v52
	v_add_f32_e32 v52, v48, v52
	v_add_f32_e32 v52, v49, v52
	v_add_f32_e32 v52, v50, v52
	v_add_f32_e32 v52, v51, v52
	v_add_f32_e32 v1, v1, v100
	v_add_f32_e32 v1, v1, v52
	v_cvt_pk_bf16_f32 v52, v68, v69
	v_cvt_pk_bf16_f32 v53, v70, v71
	v_cvt_pk_bf16_f32 v54, v72, v73
	v_cvt_pk_bf16_f32 v55, v74, v75
	v_cvt_pk_bf16_f32 v56, v76, v77
	v_cvt_pk_bf16_f32 v57, v78, v79
	v_cvt_pk_bf16_f32 v58, v80, v81
	v_cvt_pk_bf16_f32 v59, v82, v83
	v_cvt_pk_bf16_f32 v36, v36, v37
	v_cvt_pk_bf16_f32 v37, v38, v39
	v_cvt_pk_bf16_f32 v38, v40, v41
	v_cvt_pk_bf16_f32 v39, v42, v43
	v_cvt_pk_bf16_f32 v40, v44, v45
	v_cvt_pk_bf16_f32 v41, v46, v47
	v_cvt_pk_bf16_f32 v42, v48, v49
	v_cvt_pk_bf16_f32 v43, v50, v51
	v_add3_u32 v0, v0, v3, s24
	ds_read_b64_tr_b16 v[44:45],v0 offset:0
	ds_read_b64_tr_b16 v[46:47],v0 offset:512
	ds_read_b64_tr_b16 v[48:49],v0 offset:1024
	ds_read_b64_tr_b16 v[50:51],v0 offset:1536
	ds_read_b64_tr_b16 v[60:61],v0 offset:2048
	ds_read_b64_tr_b16 v[62:63],v0 offset:2560
	ds_read_b64_tr_b16 v[64:65],v0 offset:3072
	ds_read_b64_tr_b16 v[66:67],v0 offset:3584
	s_waitcnt lgkmcnt(0)
	s_nop 0
	v_mfma_f32_32x32x16_bf16 v[4:19], v[52:55], v[44:47], v[4:19]
	ds_read_b64_tr_b16 v[44:45],v0 offset:4096
	ds_read_b64_tr_b16 v[46:47],v0 offset:4608
	v_mfma_f32_32x32x16_bf16 v[4:19], v[56:59], v[48:51], v[4:19]
	ds_read_b64_tr_b16 v[48:49],v0 offset:5120
	ds_read_b64_tr_b16 v[50:51],v0 offset:5632
	v_mfma_f32_32x32x16_bf16 v[4:19], v[36:39], v[60:63], v[4:19]
	ds_read_b64_tr_b16 v[60:61],v0 offset:6144
	ds_read_b64_tr_b16 v[62:63],v0 offset:6656
	v_mfma_f32_32x32x16_bf16 v[4:19], v[40:43], v[64:67], v[4:19]
	ds_read_b64_tr_b16 v[64:65],v0 offset:7168
	ds_read_b64_tr_b16 v[66:67],v0 offset:7680
	s_waitcnt lgkmcnt(0)
	v_mfma_f32_32x32x16_bf16 v[20:35], v[52:55], v[44:47], v[20:35]
	v_mfma_f32_32x32x16_bf16 v[20:35], v[56:59], v[48:51], v[20:35]
	v_mfma_f32_32x32x16_bf16 v[20:35], v[36:39], v[60:63], v[20:35]
	v_mfma_f32_32x32x16_bf16 v[20:35], v[40:43], v[64:67], v[20:35]
	s_setprio 0
	v_mov_b32_e32 v0, v1
	s_nop 1
	v_permlane32_swap_b32_e32 v1, v0
	v_cmp_gt_u32_e32 vcc, 32, v186
	s_and_saveexec_b64 s[24:25], vcc
	s_cbranch_execz .LBB0_727
	v_lshl_add_u32 v3, v188, 2, s28
	v_add_f32_e32 v0, v1, v0
	ds_write_b32 v3, v0 offset:49280
	s_branch .LBB0_727
